# GEMM unit heads: accumulators cleared with 64-bit moves (65 instead of 128 VALU ops per wave per unit)
# speedup vs baseline: 1.0069x; 1.0047x over previous
.LBB0_121:
	s_ashr_i32 s27, s26, 31
	s_lshl_b64 s[28:29], s[26:27], 19
	s_add_u32 s28, s78, s28
	s_addc_u32 s29, s79, s29
	s_and_b64 s[30:31], s[40:41], exec
	s_cselect_b32 s1, s29, s37
	s_cselect_b32 s27, s28, s36
	s_ashr_i32 s25, s24, 31
	s_lshl_b64 s[30:31], s[24:25], 19
	s_add_u32 s30, s4, s30
	s_addc_u32 s31, s5, s31
	s_and_b64 s[40:41], s[40:41], exec
	s_cselect_b32 s25, s31, s39
	s_cselect_b32 s35, s30, s38
	s_add_u32 s36, s36, 0x40080
	s_addc_u32 s37, s37, 0
	s_add_u32 s57, s38, 0x100
	v_mov_b32_e32 v2, 0
	s_addc_u32 s58, s39, 0
	s_mov_b32 s59, -2
	v_mov_b32_e32 v3, 0
	v_mov_b64_e32 v[4:5], 0
	v_mov_b64_e32 v[6:7], 0
	v_mov_b64_e32 v[8:9], 0
	v_mov_b64_e32 v[10:11], 0
	v_mov_b64_e32 v[12:13], 0
	v_mov_b64_e32 v[14:15], 0
	v_mov_b64_e32 v[16:17], 0
	v_mov_b64_e32 v[18:19], 0
	v_mov_b64_e32 v[20:21], 0
	v_mov_b64_e32 v[22:23], 0
	v_mov_b64_e32 v[24:25], 0
	v_mov_b64_e32 v[26:27], 0
	v_mov_b64_e32 v[28:29], 0
	v_mov_b64_e32 v[30:31], 0
	v_mov_b64_e32 v[32:33], 0
	v_mov_b64_e32 v[34:35], 0
	v_mov_b64_e32 v[36:37], 0
	v_mov_b64_e32 v[38:39], 0
	v_mov_b64_e32 v[40:41], 0
	v_mov_b64_e32 v[42:43], 0
	v_mov_b64_e32 v[44:45], 0
	v_mov_b64_e32 v[46:47], 0
	v_mov_b64_e32 v[48:49], 0
	v_mov_b64_e32 v[50:51], 0
	v_mov_b64_e32 v[52:53], 0
	v_mov_b64_e32 v[54:55], 0
	v_mov_b64_e32 v[56:57], 0
	v_mov_b64_e32 v[58:59], 0
	v_mov_b64_e32 v[60:61], 0
	v_mov_b64_e32 v[62:63], 0
	v_mov_b64_e32 v[64:65], 0
	v_mov_b64_e32 v[66:67], 0
	v_mov_b64_e32 v[68:69], 0
	v_mov_b64_e32 v[70:71], 0
	v_mov_b64_e32 v[72:73], 0
	v_mov_b64_e32 v[74:75], 0
	v_mov_b64_e32 v[76:77], 0
	v_mov_b64_e32 v[78:79], 0
	v_mov_b64_e32 v[80:81], 0
	v_mov_b64_e32 v[82:83], 0
	v_mov_b64_e32 v[84:85], 0
	v_mov_b64_e32 v[86:87], 0
	v_mov_b64_e32 v[88:89], 0
	v_mov_b64_e32 v[90:91], 0
	v_mov_b64_e32 v[92:93], 0
	v_mov_b64_e32 v[94:95], 0
	v_mov_b64_e32 v[96:97], 0
	v_mov_b64_e32 v[98:99], 0
	v_mov_b64_e32 v[100:101], 0
	v_mov_b64_e32 v[102:103], 0
	v_mov_b64_e32 v[104:105], 0
	v_mov_b64_e32 v[106:107], 0
	v_mov_b64_e32 v[108:109], 0
	v_mov_b64_e32 v[110:111], 0
	v_mov_b64_e32 v[112:113], 0
	v_mov_b64_e32 v[114:115], 0
	v_mov_b64_e32 v[116:117], 0
	v_mov_b64_e32 v[118:119], 0
	v_mov_b64_e32 v[120:121], 0
	v_mov_b64_e32 v[122:123], 0
	v_mov_b64_e32 v[124:125], 0
	v_mov_b64_e32 v[126:127], 0
	v_mov_b64_e32 v[128:129], 0

.LBB0_580:
	s_ashr_i32 s11, s10, 31
	s_lshl_b64 s[12:13], s[10:11], 19
	s_add_u32 s12, s96, s12
	s_addc_u32 s13, s97, s13
	s_and_b64 s[14:15], s[24:25], exec
	s_cselect_b32 s11, s13, s19
	s_cselect_b32 s42, s12, s18
	s_ashr_i32 s9, s8, 31
	s_lshl_b64 s[14:15], s[8:9], 19
	s_add_u32 s14, s56, s14
	s_addc_u32 s15, s57, s15
	v_lshl_add_u32 v2, s16, 9, v187
	s_and_b64 s[24:25], s[24:25], exec
	v_ashrrev_i32_e32 v3, 31, v2
	s_cselect_b32 s9, s15, s23
	s_cselect_b32 s43, s14, s22
	v_lshl_add_u64 v[160:161], v[2:3], 1, s[92:93]
	s_add_u32 s44, s22, 0x100
	v_mov_b32_e32 v2, 0
	v_lshl_add_u32 v158, s20, 8, v184
	v_lshl_add_u64 v[174:175], s[18:19], 0, v[170:171]
	v_lshl_add_u64 v[176:177], s[18:19], 0, v[172:173]
	s_addc_u32 s45, s23, 0
	s_mov_b32 s46, -2
	s_mov_b64 s[20:21], 0
	v_mov_b32_e32 v3, 0
	v_mov_b64_e32 v[4:5], 0
	v_mov_b64_e32 v[6:7], 0
	v_mov_b64_e32 v[8:9], 0
	v_mov_b64_e32 v[10:11], 0
	v_mov_b64_e32 v[12:13], 0
	v_mov_b64_e32 v[14:15], 0
	v_mov_b64_e32 v[16:17], 0
	v_mov_b64_e32 v[18:19], 0
	v_mov_b64_e32 v[20:21], 0
	v_mov_b64_e32 v[22:23], 0
	v_mov_b64_e32 v[24:25], 0
	v_mov_b64_e32 v[26:27], 0
	v_mov_b64_e32 v[28:29], 0
	v_mov_b64_e32 v[30:31], 0
	v_mov_b64_e32 v[32:33], 0
	v_mov_b64_e32 v[34:35], 0
	v_mov_b64_e32 v[36:37], 0
	v_mov_b64_e32 v[38:39], 0
	v_mov_b64_e32 v[40:41], 0
	v_mov_b64_e32 v[42:43], 0
	v_mov_b64_e32 v[44:45], 0
	v_mov_b64_e32 v[46:47], 0
	v_mov_b64_e32 v[48:49], 0
	v_mov_b64_e32 v[50:51], 0
	v_mov_b64_e32 v[52:53], 0
	v_mov_b64_e32 v[54:55], 0
	v_mov_b64_e32 v[56:57], 0
	v_mov_b64_e32 v[58:59], 0
	v_mov_b64_e32 v[60:61], 0
	v_mov_b64_e32 v[62:63], 0
	v_mov_b64_e32 v[64:65], 0
	v_mov_b64_e32 v[66:67], 0
	v_mov_b64_e32 v[68:69], 0
	v_mov_b64_e32 v[70:71], 0
	v_mov_b64_e32 v[72:73], 0
	v_mov_b64_e32 v[74:75], 0
	v_mov_b64_e32 v[76:77], 0
	v_mov_b64_e32 v[78:79], 0
	v_mov_b64_e32 v[80:81], 0
	v_mov_b64_e32 v[82:83], 0
	v_mov_b64_e32 v[84:85], 0
	v_mov_b64_e32 v[86:87], 0
	v_mov_b64_e32 v[88:89], 0
	v_mov_b64_e32 v[90:91], 0
	v_mov_b64_e32 v[92:93], 0
	v_mov_b64_e32 v[94:95], 0
	v_mov_b64_e32 v[96:97], 0
	v_mov_b64_e32 v[98:99], 0
	v_mov_b64_e32 v[100:101], 0
	v_mov_b64_e32 v[102:103], 0
	v_mov_b64_e32 v[104:105], 0
	v_mov_b64_e32 v[106:107], 0
	v_mov_b64_e32 v[108:109], 0
	v_mov_b64_e32 v[110:111], 0
	v_mov_b64_e32 v[112:113], 0
	v_mov_b64_e32 v[114:115], 0
	v_mov_b64_e32 v[116:117], 0
	v_mov_b64_e32 v[118:119], 0
	v_mov_b64_e32 v[120:121], 0
	v_mov_b64_e32 v[122:123], 0
	v_mov_b64_e32 v[124:125], 0
	v_mov_b64_e32 v[126:127], 0
	v_mov_b64_e32 v[128:129], 0
	s_branch .LBB0_582

.LBB0_670:
	s_ashr_i32 s21, s20, 31
	s_lshl_b64 s[22:23], s[20:21], 19
	s_add_u32 s22, s78, s22
	s_addc_u32 s23, s79, s23
	s_and_b64 s[24:25], s[26:27], exec
	s_cselect_b32 s5, s23, s9
	s_cselect_b32 s7, s22, s8
	s_ashr_i32 s19, s18, 31
	s_lshl_b64 s[24:25], s[18:19], 19
	s_add_u32 s24, s66, s24
	s_addc_u32 s25, s67, s25
	s_and_b64 s[26:27], s[26:27], exec
	s_cselect_b32 s19, s25, s11
	s_cselect_b32 s21, s24, s10
	s_add_u32 s8, s8, 0x40080
	s_addc_u32 s9, s9, 0
	s_add_u32 s56, s10, 0x100
	v_mov_b32_e32 v2, 0
	s_addc_u32 s57, s11, 0
	s_mov_b32 s58, -2
	s_waitcnt lgkmcnt(0)
	v_mov_b32_e32 v3, 0
	v_mov_b64_e32 v[4:5], 0
	v_mov_b64_e32 v[6:7], 0
	v_mov_b64_e32 v[8:9], 0
	v_mov_b64_e32 v[10:11], 0
	v_mov_b64_e32 v[12:13], 0
	v_mov_b64_e32 v[14:15], 0
	v_mov_b64_e32 v[16:17], 0
	v_mov_b64_e32 v[18:19], 0
	v_mov_b64_e32 v[20:21], 0
	v_mov_b64_e32 v[22:23], 0
	v_mov_b64_e32 v[24:25], 0
	v_mov_b64_e32 v[26:27], 0
	v_mov_b64_e32 v[28:29], 0
	v_mov_b64_e32 v[30:31], 0
	v_mov_b64_e32 v[32:33], 0
	v_mov_b64_e32 v[34:35], 0
	v_mov_b64_e32 v[36:37], 0
	v_mov_b64_e32 v[38:39], 0
	v_mov_b64_e32 v[40:41], 0
	v_mov_b64_e32 v[42:43], 0
	v_mov_b64_e32 v[44:45], 0
	v_mov_b64_e32 v[46:47], 0
	v_mov_b64_e32 v[48:49], 0
	v_mov_b64_e32 v[50:51], 0
	v_mov_b64_e32 v[52:53], 0
	v_mov_b64_e32 v[54:55], 0
	v_mov_b64_e32 v[56:57], 0
	v_mov_b64_e32 v[58:59], 0
	v_mov_b64_e32 v[60:61], 0
	v_mov_b64_e32 v[62:63], 0
	v_mov_b64_e32 v[64:65], 0
	v_mov_b64_e32 v[66:67], 0
	v_mov_b64_e32 v[68:69], 0
	v_mov_b64_e32 v[70:71], 0
	v_mov_b64_e32 v[72:73], 0
	v_mov_b64_e32 v[74:75], 0
	v_mov_b64_e32 v[76:77], 0
	v_mov_b64_e32 v[78:79], 0
	v_mov_b64_e32 v[80:81], 0
	v_mov_b64_e32 v[82:83], 0
	v_mov_b64_e32 v[84:85], 0
	v_mov_b64_e32 v[86:87], 0
	v_mov_b64_e32 v[88:89], 0
	v_mov_b64_e32 v[90:91], 0
	v_mov_b64_e32 v[92:93], 0
	v_mov_b64_e32 v[94:95], 0
	v_mov_b64_e32 v[96:97], 0
	v_mov_b64_e32 v[98:99], 0
	v_mov_b64_e32 v[100:101], 0
	v_mov_b64_e32 v[102:103], 0
	v_mov_b64_e32 v[104:105], 0
	v_mov_b64_e32 v[106:107], 0
	v_mov_b64_e32 v[108:109], 0
	v_mov_b64_e32 v[110:111], 0
	v_mov_b64_e32 v[112:113], 0
	v_mov_b64_e32 v[114:115], 0
	v_mov_b64_e32 v[116:117], 0
	v_mov_b64_e32 v[118:119], 0
	v_mov_b64_e32 v[120:121], 0
	v_mov_b64_e32 v[122:123], 0
	v_mov_b64_e32 v[124:125], 0
	v_mov_b64_e32 v[126:127], 0
	v_mov_b64_e32 v[128:129], 0

.LBB0_840:
	s_ashr_i32 s11, s10, 31
	s_lshl_b64 s[12:13], s[10:11], 19
	s_add_u32 s12, s96, s12
	s_addc_u32 s13, s97, s13
	s_and_b64 s[14:15], s[24:25], exec
	s_cselect_b32 s11, s13, s21
	s_cselect_b32 s41, s12, s20
	s_ashr_i32 s9, s8, 31
	s_lshl_b64 s[14:15], s[8:9], 19
	s_add_u32 s14, s50, s14
	s_addc_u32 s15, s51, s15
	s_and_b64 s[24:25], s[24:25], exec
	s_cselect_b32 s9, s15, s23
	s_cselect_b32 s42, s14, s22
	s_add_u32 s20, s20, 0x40080
	s_addc_u32 s21, s21, 0
	s_add_u32 s43, s22, 0x100
	v_mov_b32_e32 v2, 0
	s_addc_u32 s44, s23, 0
	s_mov_b32 s45, -2
	v_mov_b32_e32 v3, 0
	v_mov_b64_e32 v[4:5], 0
	v_mov_b64_e32 v[6:7], 0
	v_mov_b64_e32 v[8:9], 0
	v_mov_b64_e32 v[10:11], 0
	v_mov_b64_e32 v[12:13], 0
	v_mov_b64_e32 v[14:15], 0
	v_mov_b64_e32 v[16:17], 0
	v_mov_b64_e32 v[18:19], 0
	v_mov_b64_e32 v[20:21], 0
	v_mov_b64_e32 v[22:23], 0
	v_mov_b64_e32 v[24:25], 0
	v_mov_b64_e32 v[26:27], 0
	v_mov_b64_e32 v[28:29], 0
	v_mov_b64_e32 v[30:31], 0
	v_mov_b64_e32 v[32:33], 0
	v_mov_b64_e32 v[34:35], 0
	v_mov_b64_e32 v[36:37], 0
	v_mov_b64_e32 v[38:39], 0
	v_mov_b64_e32 v[40:41], 0
	v_mov_b64_e32 v[42:43], 0
	v_mov_b64_e32 v[44:45], 0
	v_mov_b64_e32 v[46:47], 0
	v_mov_b64_e32 v[48:49], 0
	v_mov_b64_e32 v[50:51], 0
	v_mov_b64_e32 v[52:53], 0
	v_mov_b64_e32 v[54:55], 0
	v_mov_b64_e32 v[56:57], 0
	v_mov_b64_e32 v[58:59], 0
	v_mov_b64_e32 v[60:61], 0
	v_mov_b64_e32 v[62:63], 0
	v_mov_b64_e32 v[64:65], 0
	v_mov_b64_e32 v[66:67], 0
	v_mov_b64_e32 v[68:69], 0
	v_mov_b64_e32 v[70:71], 0
	v_mov_b64_e32 v[72:73], 0
	v_mov_b64_e32 v[74:75], 0
	v_mov_b64_e32 v[76:77], 0
	v_mov_b64_e32 v[78:79], 0
	v_mov_b64_e32 v[80:81], 0
	v_mov_b64_e32 v[82:83], 0
	v_mov_b64_e32 v[84:85], 0
	v_mov_b64_e32 v[86:87], 0
	v_mov_b64_e32 v[88:89], 0
	v_mov_b64_e32 v[90:91], 0
	v_mov_b64_e32 v[92:93], 0
	v_mov_b64_e32 v[94:95], 0
	v_mov_b64_e32 v[96:97], 0
	v_mov_b64_e32 v[98:99], 0
	v_mov_b64_e32 v[100:101], 0
	v_mov_b64_e32 v[102:103], 0
	v_mov_b64_e32 v[104:105], 0
	v_mov_b64_e32 v[106:107], 0
	v_mov_b64_e32 v[108:109], 0
	v_mov_b64_e32 v[110:111], 0
	v_mov_b64_e32 v[112:113], 0
	v_mov_b64_e32 v[114:115], 0
	v_mov_b64_e32 v[116:117], 0
	v_mov_b64_e32 v[118:119], 0
	v_mov_b64_e32 v[120:121], 0
	v_mov_b64_e32 v[122:123], 0
	v_mov_b64_e32 v[124:125], 0
	v_mov_b64_e32 v[126:127], 0
	v_mov_b64_e32 v[128:129], 0

.LBB0_927:
	s_add_u32 s10, s10, 0xb0080
	s_addc_u32 s11, s11, 0
	s_add_u32 s44, s12, 0x100
	v_mov_b32_e32 v2, 0
	s_addc_u32 s45, s13, 0
	s_mov_b32 s46, -2
	v_mov_b32_e32 v3, 0
	v_mov_b64_e32 v[4:5], 0
	v_mov_b64_e32 v[6:7], 0
	v_mov_b64_e32 v[8:9], 0
	v_mov_b64_e32 v[10:11], 0
	v_mov_b64_e32 v[12:13], 0
	v_mov_b64_e32 v[14:15], 0
	v_mov_b64_e32 v[16:17], 0
	v_mov_b64_e32 v[18:19], 0
	v_mov_b64_e32 v[20:21], 0
	v_mov_b64_e32 v[22:23], 0
	v_mov_b64_e32 v[24:25], 0
	v_mov_b64_e32 v[26:27], 0
	v_mov_b64_e32 v[28:29], 0
	v_mov_b64_e32 v[30:31], 0
	v_mov_b64_e32 v[32:33], 0
	v_mov_b64_e32 v[34:35], 0
	v_mov_b64_e32 v[36:37], 0
	v_mov_b64_e32 v[38:39], 0
	v_mov_b64_e32 v[40:41], 0
	v_mov_b64_e32 v[42:43], 0
	v_mov_b64_e32 v[44:45], 0
	v_mov_b64_e32 v[46:47], 0
	v_mov_b64_e32 v[48:49], 0
	v_mov_b64_e32 v[50:51], 0
	v_mov_b64_e32 v[52:53], 0
	v_mov_b64_e32 v[54:55], 0
	v_mov_b64_e32 v[56:57], 0
	v_mov_b64_e32 v[58:59], 0
	v_mov_b64_e32 v[60:61], 0
	v_mov_b64_e32 v[62:63], 0
	v_mov_b64_e32 v[64:65], 0
	v_mov_b64_e32 v[66:67], 0
	v_mov_b64_e32 v[68:69], 0
	v_mov_b64_e32 v[70:71], 0
	v_mov_b64_e32 v[72:73], 0
	v_mov_b64_e32 v[74:75], 0
	v_mov_b64_e32 v[76:77], 0
	v_mov_b64_e32 v[78:79], 0
	v_mov_b64_e32 v[80:81], 0
	v_mov_b64_e32 v[82:83], 0
	v_mov_b64_e32 v[84:85], 0
	v_mov_b64_e32 v[86:87], 0
	v_mov_b64_e32 v[88:89], 0
	v_mov_b64_e32 v[90:91], 0
	v_mov_b64_e32 v[92:93], 0
	v_mov_b64_e32 v[94:95], 0
	v_mov_b64_e32 v[96:97], 0
	v_mov_b64_e32 v[98:99], 0
	v_mov_b64_e32 v[100:101], 0
	v_mov_b64_e32 v[102:103], 0
	v_mov_b64_e32 v[104:105], 0
	v_mov_b64_e32 v[106:107], 0
	v_mov_b64_e32 v[108:109], 0
	v_mov_b64_e32 v[110:111], 0
	v_mov_b64_e32 v[112:113], 0
	v_mov_b64_e32 v[114:115], 0
	v_mov_b64_e32 v[116:117], 0
	v_mov_b64_e32 v[118:119], 0
	v_mov_b64_e32 v[120:121], 0
	v_mov_b64_e32 v[122:123], 0
	v_mov_b64_e32 v[124:125], 0
	v_mov_b64_e32 v[126:127], 0
	v_mov_b64_e32 v[128:129], 0
